# norm phases: loop-invariant gamma loads hoisted out of the row loop (8 serialized load-wait round trips per iteration removed)
# speedup vs baseline: 1.1526x; 1.0021x over previous
; DEVQ unsigned pk2(float lo, float hi) { return f2bf(lo) | (f2bf(hi) << 16); }
; DEVQ void row_finish(const RowV& r, const float* g, bf16* urow, float* hcopy, const float* hbias, int lane) {
;     const float rstd = 1.0f / sqrtf(wave_sum(r.ss) * (1.0f / D) + RMS_EPS);
; #pragma unroll
;     for (int j = 0; j < 4; ++j) { const f32x4 gv = ((const f32x4*)g)[lane + 64 * j];
;         if (hcopy) ((f32x4*)hcopy)[lane + 64 * j] = r.v[j] + ((const f32x4*)hbias)[lane + 64 * j];
;         ((unsigned long long*)urow)[lane + 64 * j] = (unsigned long long)pk2(r.v[j].x * rstd * gv.x, r.v[j].y * rstd * gv.y) | ((unsigned long long)pk2(r.v[j].z * rstd * gv.z, r.v[j].w * rstd * gv.w) << 32); }
; }
; __global__ void __launch_bounds__(NTHR) hyena_swa_fwd(Params P) {
;     ...
;             if (ph == 10 && G == 256 && bid >= 136) {
;                 const float* gn = Q.in[3] + D; const int lw = (bid - 136) * NWAVES + wave;
;                 for (int m = 2 * lw; m < CH1; m += 2 * 120 * NWAVES) {
;                     const RowV ra = row_load(H + (size_t)m * D, lane), rb = row_load(H + (size_t)(m + 1) * D, lane);
;                     row_finish(ra, gn, U + (size_t)m * D, nullptr, nullptr, lane); row_finish(rb, gn, U + (size_t)(m + 1) * D, nullptr, nullptr, lane); }
;             }
.LBB0_180:
	v_readlane_b32 s0, v255, 32
	s_cmp_eq_u32 s0, 10
	s_cselect_b64 s[0:1], -1, 0
	s_and_b64 s[0:1], s[0:1], s[4:5]
	s_and_b64 s[0:1], s[0:1], s[14:15]
	v_readlane_b32 s18, v255, 28
	s_andn2_b64 vcc, exec, s[0:1]
	s_mov_b64 s[14:15], 0x780000
	v_readlane_b32 s19, v255, 29
	s_cbranch_vccnz .LBB0_184
	v_readlane_b32 s0, v255, 18
	s_lshl_b32 s0, s0, 1
	s_addk_i32 s0, 0xf780
	s_cmp_gt_i32 s0, 0x9fff
	s_cbranch_scc1 .LBB0_184
	v_and_b32_e32 v0, 64, v185
	v_add_u32_e32 v0, 64, v0
	v_xor_b32_e32 v1, 1, v185
	v_cmp_lt_i32_e32 vcc, v1, v0
	v_readlane_b32 s2, v255, 35
	v_readlane_b32 s3, v255, 36
	v_cndmask_b32_e32 v1, v185, v1, vcc
	v_lshlrev_b32_e32 v44, 2, v1
	v_xor_b32_e32 v1, 2, v185
	v_cmp_lt_i32_e32 vcc, v1, v0
	s_add_u32 s2, s2, 0x1000
	v_lshlrev_b32_e32 v128, 4, v136
	v_cndmask_b32_e32 v1, v185, v1, vcc
	v_lshlrev_b32_e32 v45, 2, v1
	v_xor_b32_e32 v1, 4, v185
	v_cmp_lt_i32_e32 vcc, v1, v0
	s_addc_u32 s3, s3, 0
	v_lshl_add_u64 v[32:33], s[2:3], 0, v[128:129]
	v_cndmask_b32_e32 v1, v185, v1, vcc
	v_lshlrev_b32_e32 v46, 2, v1
	v_xor_b32_e32 v1, 8, v185
	v_cmp_lt_i32_e32 vcc, v1, v0
	s_nop 1
	v_cndmask_b32_e32 v1, v185, v1, vcc
	v_lshlrev_b32_e32 v47, 2, v1
	v_xor_b32_e32 v1, 16, v185
	v_cmp_lt_i32_e32 vcc, v1, v0
	s_nop 1
	v_cndmask_b32_e32 v1, v185, v1, vcc
	v_lshlrev_b32_e32 v48, 2, v1
	v_xor_b32_e32 v1, 32, v185
	v_cmp_lt_i32_e32 vcc, v1, v0
	s_nop 1
	v_cndmask_b32_e32 v0, v185, v1, vcc
	v_lshlrev_b32_e32 v49, 2, v0
	v_or_b32_e32 v0, 0x400, v128
	v_mov_b32_e32 v1, v129
	v_lshl_add_u64 v[34:35], s[2:3], 0, v[0:1]
	v_or_b32_e32 v0, 0x800, v128
	v_lshl_add_u64 v[36:37], s[2:3], 0, v[0:1]
	v_or_b32_e32 v0, 0xc00, v128
	v_lshl_add_u64 v[38:39], s[2:3], 0, v[0:1]
	v_readlane_b32 s2, v255, 37
	s_lshl_b32 s1, s2, 4
	v_readlane_b32 s2, v255, 17
	s_lshl_b32 s2, s2, 1
	s_add_i32 s1, s1, s2
	v_readlane_b32 s3, v255, 38
	s_add_i32 s4, s1, 0xfffff000
	s_ashr_i32 s1, s0, 31
	s_lshl_b64 s[2:3], s[0:1], 11
	s_lshl_b64 s[0:1], s[0:1], 12
	v_lshl_or_b32 v40, v136, 3, s2
	v_mov_b32_e32 v41, s3
	v_or_b32_e32 v42, s0, v128
	v_mov_b32_e32 v43, s1
	flat_load_dwordx4 v[64:67], v[32:33]
	flat_load_dwordx4 v[68:71], v[34:35]
	flat_load_dwordx4 v[72:75], v[36:37]
	flat_load_dwordx4 v[76:79], v[38:39]
.LBB0_183:
	v_lshl_add_u64 v[0:1], s[18:19], 0, v[42:43]
	v_add_co_u32_e32 v2, vcc, 0x3200000, v0
	s_addk_i32 s4, 0x780
	s_nop 0
	v_addc_co_u32_e32 v3, vcc, 0, v1, vcc
	flat_load_dwordx4 v[28:31], v[2:3]
	flat_load_dwordx4 v[24:27], v[2:3] offset:1024
	flat_load_dwordx4 v[20:23], v[2:3] offset:2048
	flat_load_dwordx4 v[16:19], v[2:3] offset:3072
	v_add_co_u32_e32 v0, vcc, s30, v0
	v_lshl_add_u64 v[42:43], v[42:43], 0, s[14:15]
	s_nop 0
	v_addc_co_u32_e32 v1, vcc, 0, v1, vcc
	s_cmp_gt_i32 s4, 0x987f
	s_waitcnt vmcnt(0) lgkmcnt(0)
	v_mul_f32_e32 v2, v29, v29
	v_mul_f32_e32 v3, v31, v31
	v_fmac_f32_e32 v2, v28, v28
	v_fmac_f32_e32 v3, v30, v30
	v_add_f32_e32 v2, v2, v3
	v_mul_f32_e32 v3, v25, v25
	v_mul_f32_e32 v4, v27, v27
	v_fmac_f32_e32 v3, v24, v24
	v_fmac_f32_e32 v4, v26, v26
	v_add_f32_e32 v3, v3, v4
	v_add_f32_e32 v2, v2, v3
	v_mul_f32_e32 v3, v21, v21
	v_mul_f32_e32 v4, v23, v23
	v_fmac_f32_e32 v3, v20, v20
	v_fmac_f32_e32 v4, v22, v22
	v_add_f32_e32 v3, v3, v4
	v_add_f32_e32 v2, v2, v3
	v_mul_f32_e32 v3, v17, v17
	v_mul_f32_e32 v4, v19, v19
	v_fmac_f32_e32 v3, v16, v16
	v_fmac_f32_e32 v4, v18, v18
	v_add_f32_e32 v3, v3, v4
	v_add_f32_e32 v51, v2, v3
	flat_load_dwordx4 v[12:15], v[0:1]
	flat_load_dwordx4 v[8:11], v[0:1] offset:1024
	flat_load_dwordx4 v[4:7], v[0:1] offset:2048
	s_nop 0
	flat_load_dwordx4 v[0:3], v[0:1] offset:3072
	s_waitcnt vmcnt(0) lgkmcnt(0)
	v_mul_f32_e32 v50, v13, v13
	v_mul_f32_e32 v52, v15, v15
	v_fmac_f32_e32 v50, v12, v12
	v_fmac_f32_e32 v52, v14, v14
	v_add_f32_e32 v50, v50, v52
	v_mul_f32_e32 v52, v9, v9
	v_mul_f32_e32 v53, v11, v11
	v_fmac_f32_e32 v52, v8, v8
	v_fmac_f32_e32 v53, v10, v10
	v_add_f32_e32 v52, v52, v53
	v_add_f32_e32 v50, v50, v52
	v_mul_f32_e32 v52, v5, v5
	v_mul_f32_e32 v53, v7, v7
	v_fmac_f32_e32 v52, v4, v4
	v_fmac_f32_e32 v53, v6, v6
	v_add_f32_e32 v52, v52, v53
	v_add_f32_e32 v50, v50, v52
	v_mul_f32_e32 v52, v1, v1
	v_mul_f32_e32 v53, v3, v3
	v_fmac_f32_e32 v52, v0, v0
	v_fmac_f32_e32 v53, v2, v2
	v_add_f32_e32 v52, v52, v53
	v_add_f32_e32 v50, v50, v52
	ds_bpermute_b32 v52, v44, v51
	s_waitcnt lgkmcnt(0)
	v_add_f32_e32 v51, v51, v52
	ds_bpermute_b32 v52, v45, v51
	s_waitcnt lgkmcnt(0)
	v_add_f32_e32 v51, v51, v52
	ds_bpermute_b32 v52, v46, v51
	s_waitcnt lgkmcnt(0)
	v_add_f32_e32 v51, v51, v52
	ds_bpermute_b32 v52, v47, v51
	s_waitcnt lgkmcnt(0)
	v_add_f32_e32 v51, v51, v52
	ds_bpermute_b32 v52, v48, v51
	s_waitcnt lgkmcnt(0)
	v_add_f32_e32 v51, v51, v52
	ds_bpermute_b32 v52, v49, v51
	s_waitcnt lgkmcnt(0)
; DEVQ unsigned pk2(float lo, float hi) { return f2bf(lo) | (f2bf(hi) << 16); }
; DEVQ void row_finish(const RowV& r, const float* g, bf16* urow, float* hcopy, const float* hbias, int lane) {
;     const float rstd = 1.0f / sqrtf(wave_sum(r.ss) * (1.0f / D) + RMS_EPS);
; #pragma unroll
;     for (int j = 0; j < 4; ++j) { const f32x4 gv = ((const f32x4*)g)[lane + 64 * j];
;         if (hcopy) ((f32x4*)hcopy)[lane + 64 * j] = r.v[j] + ((const f32x4*)hbias)[lane + 64 * j];
;         ((unsigned long long*)urow)[lane + 64 * j] = (unsigned long long)pk2(r.v[j].x * rstd * gv.x, r.v[j].y * rstd * gv.y) | ((unsigned long long)pk2(r.v[j].z * rstd * gv.z, r.v[j].w * rstd * gv.w) << 32); }
; }
	v_add_f32_e32 v51, v51, v52
	v_fmamk_f32 v51, v51, 0x3a800000, v178
	v_cmp_gt_f32_e32 vcc, s28, v51
	v_mul_f32_e32 v52, 0x4f800000, v51
	s_nop 0
	v_cndmask_b32_e32 v51, v51, v52, vcc
	v_sqrt_f32_e32 v52, v51
	s_nop 0
	v_add_u32_e32 v53, -1, v52
	v_fma_f32 v54, -v53, v52, v51
	v_cmp_ge_f32_e64 s[0:1], 0, v54
	v_add_u32_e32 v54, 1, v52
	s_nop 0
	v_cndmask_b32_e64 v53, v52, v53, s[0:1]
	v_fma_f32 v52, -v54, v52, v51
	v_cmp_lt_f32_e64 s[0:1], 0, v52
	s_nop 1
	v_cndmask_b32_e64 v52, v53, v54, s[0:1]
	v_mul_f32_e32 v53, 0x37800000, v52
	v_cndmask_b32_e32 v52, v52, v53, vcc
	v_cmp_class_f32_e32 vcc, v51, v179
	s_nop 1
	v_cndmask_b32_e32 v51, v52, v51, vcc
	v_div_scale_f32 v52, s[0:1], v51, v51, 1.0
	v_rcp_f32_e32 v53, v52
	s_nop 0
	v_fma_f32 v54, -v52, v53, 1.0
	v_fmac_f32_e32 v53, v54, v53
	v_div_scale_f32 v54, vcc, 1.0, v51, 1.0
	v_mul_f32_e32 v55, v54, v53
	v_fma_f32 v56, -v52, v55, v54
	v_fmac_f32_e32 v55, v56, v53
	v_fma_f32 v52, -v52, v55, v54
	v_div_fmas_f32 v52, v52, v53, v55
	v_div_fixup_f32 v51, v52, v51, 1.0
	v_mul_f32_e32 v28, v28, v51
	v_mul_f32_e32 v29, v29, v51
	v_mul_f32_e32 v24, v24, v51
	v_mul_f32_e32 v25, v25, v51
	v_mul_f32_e32 v20, v20, v51
	v_mul_f32_e32 v21, v21, v51
	v_mul_f32_e32 v16, v16, v51
	v_mul_f32_e32 v17, v17, v51
	v_mul_f32_e32 v28, v64, v28
	v_mul_f32_e32 v29, v65, v29
	v_bfe_u32 v52, v28, 16, 1
	v_add3_u32 v28, v28, v52, s60
	v_bfe_u32 v52, v29, 16, 1
	v_lshrrev_b32_e32 v28, 16, v28
	v_add3_u32 v29, v29, v52, s60
	v_and_or_b32 v52, v29, s61, v28
	v_mul_f32_e32 v28, v30, v51
	v_mul_f32_e32 v28, v66, v28
	v_mul_f32_e32 v29, v31, v51
	v_mul_f32_e32 v29, v67, v29
	v_bfe_u32 v30, v28, 16, 1
	v_add3_u32 v28, v28, v30, s60
	v_bfe_u32 v30, v29, 16, 1
	v_lshrrev_b32_e32 v28, 16, v28
	v_add3_u32 v29, v29, v30, s60
	v_and_or_b32 v53, v29, s61, v28
	v_lshl_add_u64 v[28:29], s[18:19], 0, v[40:41]
	v_add_co_u32_e32 v28, vcc, s31, v28
	s_nop 1
	v_addc_co_u32_e32 v29, vcc, 0, v29, vcc
	flat_store_dwordx2 v[28:29], v[52:53]
	v_mul_f32_e32 v24, v68, v24
	v_mul_f32_e32 v25, v69, v25
	v_bfe_u32 v30, v24, 16, 1
	v_add3_u32 v24, v24, v30, s60
	v_bfe_u32 v30, v25, 16, 1
	v_lshrrev_b32_e32 v24, 16, v24
	v_add3_u32 v25, v25, v30, s60
	v_and_or_b32 v24, v25, s61, v24
	v_mul_f32_e32 v25, v26, v51
	v_mul_f32_e32 v25, v70, v25
	v_mul_f32_e32 v26, v27, v51
	v_mul_f32_e32 v26, v71, v26
	v_bfe_u32 v27, v25, 16, 1
	v_add3_u32 v25, v25, v27, s60
	v_bfe_u32 v27, v26, 16, 1
	v_lshrrev_b32_e32 v25, 16, v25
	v_add3_u32 v26, v26, v27, s60
	v_and_or_b32 v25, v26, s61, v25
	flat_store_dwordx2 v[28:29], v[24:25] offset:512
	v_mul_f32_e32 v20, v72, v20
	v_mul_f32_e32 v21, v73, v21
	v_bfe_u32 v24, v20, 16, 1
	v_add3_u32 v20, v20, v24, s60
	v_bfe_u32 v24, v21, 16, 1
	v_lshrrev_b32_e32 v20, 16, v20
	v_add3_u32 v21, v21, v24, s60
	v_and_or_b32 v20, v21, s61, v20
	v_mul_f32_e32 v21, v22, v51
	v_mul_f32_e32 v21, v74, v21
	v_mul_f32_e32 v22, v23, v51
	v_mul_f32_e32 v22, v75, v22
	v_bfe_u32 v23, v21, 16, 1
	v_add3_u32 v21, v21, v23, s60
	v_bfe_u32 v23, v22, 16, 1
	v_lshrrev_b32_e32 v21, 16, v21
	v_add3_u32 v22, v22, v23, s60
	v_and_or_b32 v21, v22, s61, v21
	flat_store_dwordx2 v[28:29], v[20:21] offset:1024
	v_mul_f32_e32 v16, v16, v76
	v_mul_f32_e32 v17, v17, v77
	v_bfe_u32 v20, v16, 16, 1
	v_add3_u32 v16, v16, v20, s60
	v_bfe_u32 v20, v17, 16, 1
	v_lshrrev_b32_e32 v16, 16, v16
	v_add3_u32 v17, v17, v20, s60
	v_and_or_b32 v16, v17, s61, v16
	v_mul_f32_e32 v17, v18, v51
	v_mul_f32_e32 v17, v17, v78
	v_mul_f32_e32 v18, v19, v51
	v_mul_f32_e32 v18, v18, v79
	v_bfe_u32 v19, v17, 16, 1
	v_add3_u32 v17, v17, v19, s60
	v_bfe_u32 v19, v18, 16, 1
	v_lshrrev_b32_e32 v17, 16, v17
	v_add3_u32 v18, v18, v19, s60
	v_and_or_b32 v17, v18, s61, v17
	flat_store_dwordx2 v[28:29], v[16:17] offset:1536
	ds_bpermute_b32 v16, v44, v50
	s_waitcnt lgkmcnt(0)
	v_add_f32_e32 v16, v50, v16
	ds_bpermute_b32 v17, v45, v16
	s_waitcnt lgkmcnt(0)
; DEVQ unsigned pk2(float lo, float hi) { return f2bf(lo) | (f2bf(hi) << 16); }
; DEVQ void row_finish(const RowV& r, const float* g, bf16* urow, float* hcopy, const float* hbias, int lane) {
;     const float rstd = 1.0f / sqrtf(wave_sum(r.ss) * (1.0f / D) + RMS_EPS);
; #pragma unroll
;     for (int j = 0; j < 4; ++j) { const f32x4 gv = ((const f32x4*)g)[lane + 64 * j];
;         if (hcopy) ((f32x4*)hcopy)[lane + 64 * j] = r.v[j] + ((const f32x4*)hbias)[lane + 64 * j];
;         ((unsigned long long*)urow)[lane + 64 * j] = (unsigned long long)pk2(r.v[j].x * rstd * gv.x, r.v[j].y * rstd * gv.y) | ((unsigned long long)pk2(r.v[j].z * rstd * gv.z, r.v[j].w * rstd * gv.w) << 32); }
; }
	v_add_f32_e32 v16, v16, v17
	ds_bpermute_b32 v17, v46, v16
	s_waitcnt lgkmcnt(0)
	v_add_f32_e32 v16, v16, v17
	ds_bpermute_b32 v17, v47, v16
	s_waitcnt lgkmcnt(0)
	v_add_f32_e32 v16, v16, v17
	ds_bpermute_b32 v17, v48, v16
	s_waitcnt lgkmcnt(0)
	v_add_f32_e32 v16, v16, v17
	ds_bpermute_b32 v17, v49, v16
	s_waitcnt lgkmcnt(0)
	v_add_f32_e32 v16, v16, v17
	v_fmamk_f32 v16, v16, 0x3a800000, v178
	v_cmp_gt_f32_e32 vcc, s28, v16
	v_mul_f32_e32 v17, 0x4f800000, v16
	s_nop 0
	v_cndmask_b32_e32 v16, v16, v17, vcc
	v_sqrt_f32_e32 v17, v16
	s_nop 0
	v_add_u32_e32 v18, -1, v17
	v_fma_f32 v19, -v18, v17, v16
	v_cmp_ge_f32_e64 s[0:1], 0, v19
	v_add_u32_e32 v19, 1, v17
	s_nop 0
	v_cndmask_b32_e64 v18, v17, v18, s[0:1]
	v_fma_f32 v17, -v19, v17, v16
	v_cmp_lt_f32_e64 s[0:1], 0, v17
	s_nop 1
	v_cndmask_b32_e64 v17, v18, v19, s[0:1]
	v_mul_f32_e32 v18, 0x37800000, v17
	v_cndmask_b32_e32 v17, v17, v18, vcc
	v_cmp_class_f32_e32 vcc, v16, v179
	s_nop 1
	v_cndmask_b32_e32 v16, v17, v16, vcc
	v_div_scale_f32 v17, s[0:1], v16, v16, 1.0
	v_rcp_f32_e32 v18, v17
	s_mov_b64 s[0:1], 0x3c0000
	v_lshl_add_u64 v[40:41], v[40:41], 0, s[0:1]
	v_fma_f32 v19, -v17, v18, 1.0
	v_fmac_f32_e32 v18, v19, v18
	v_div_scale_f32 v19, vcc, 1.0, v16, 1.0
	v_mul_f32_e32 v20, v19, v18
	v_fma_f32 v21, -v17, v20, v19
	v_fmac_f32_e32 v20, v21, v18
	v_fma_f32 v17, -v17, v20, v19
	v_div_fmas_f32 v17, v17, v18, v20
	v_div_fixup_f32 v16, v17, v16, 1.0
	v_mul_f32_e32 v12, v12, v16
	v_mul_f32_e32 v13, v13, v16
	v_mul_f32_e32 v8, v8, v16
	v_mul_f32_e32 v9, v9, v16
	v_mul_f32_e32 v4, v4, v16
	v_mul_f32_e32 v5, v5, v16
	v_mul_f32_e32 v0, v0, v16
	v_mul_f32_e32 v1, v1, v16
	v_mul_f32_e32 v12, v64, v12
	v_mul_f32_e32 v13, v65, v13
	v_bfe_u32 v17, v12, 16, 1
	v_add3_u32 v12, v12, v17, s60
	v_bfe_u32 v17, v13, 16, 1
	v_lshrrev_b32_e32 v12, 16, v12
	v_add3_u32 v13, v13, v17, s60
	v_and_or_b32 v12, v13, s61, v12
	v_mul_f32_e32 v13, v14, v16
	v_mul_f32_e32 v13, v66, v13
	v_mul_f32_e32 v14, v15, v16
	v_mul_f32_e32 v14, v67, v14
	v_bfe_u32 v15, v13, 16, 1
	v_add3_u32 v13, v13, v15, s60
	v_bfe_u32 v15, v14, 16, 1
	v_lshrrev_b32_e32 v13, 16, v13
	v_add3_u32 v14, v14, v15, s60
	v_and_or_b32 v13, v14, s61, v13
	flat_store_dwordx2 v[28:29], v[12:13] offset:2048
	v_mul_f32_e32 v8, v68, v8
	v_mul_f32_e32 v9, v69, v9
	v_bfe_u32 v12, v8, 16, 1
	v_add3_u32 v8, v8, v12, s60
	v_bfe_u32 v12, v9, 16, 1
	v_lshrrev_b32_e32 v8, 16, v8
	v_add3_u32 v9, v9, v12, s60
	v_and_or_b32 v8, v9, s61, v8
	v_mul_f32_e32 v9, v10, v16
	v_mul_f32_e32 v9, v70, v9
	v_mul_f32_e32 v10, v11, v16
	v_mul_f32_e32 v10, v71, v10
	v_bfe_u32 v11, v9, 16, 1
	v_add3_u32 v9, v9, v11, s60
	v_bfe_u32 v11, v10, 16, 1
	v_lshrrev_b32_e32 v9, 16, v9
	v_add3_u32 v10, v10, v11, s60
	v_and_or_b32 v9, v10, s61, v9
	flat_store_dwordx2 v[28:29], v[8:9] offset:2560
	v_mul_f32_e32 v4, v72, v4
	v_mul_f32_e32 v5, v73, v5
	v_bfe_u32 v8, v4, 16, 1
	v_add3_u32 v4, v4, v8, s60
	v_bfe_u32 v8, v5, 16, 1
	v_lshrrev_b32_e32 v4, 16, v4
	v_add3_u32 v5, v5, v8, s60
	v_and_or_b32 v4, v5, s61, v4
	v_mul_f32_e32 v5, v6, v16
	v_mul_f32_e32 v5, v74, v5
	v_mul_f32_e32 v6, v7, v16
	v_mul_f32_e32 v6, v75, v6
	v_bfe_u32 v7, v5, 16, 1
	v_add3_u32 v5, v5, v7, s60
	v_bfe_u32 v7, v6, 16, 1
	v_lshrrev_b32_e32 v5, 16, v5
	v_add3_u32 v6, v6, v7, s60
	v_and_or_b32 v5, v6, s61, v5
	flat_store_dwordx2 v[28:29], v[4:5] offset:3072
	v_mul_f32_e32 v0, v0, v76
	v_mul_f32_e32 v1, v1, v77
	v_bfe_u32 v4, v0, 16, 1
	v_add3_u32 v0, v0, v4, s60
	v_bfe_u32 v4, v1, 16, 1
	v_lshrrev_b32_e32 v0, 16, v0
	v_add3_u32 v1, v1, v4, s60
	v_and_or_b32 v0, v1, s61, v0
	v_mul_f32_e32 v1, v2, v16
	v_mul_f32_e32 v1, v1, v78
	v_mul_f32_e32 v2, v3, v16
	v_mul_f32_e32 v2, v2, v79
	v_bfe_u32 v3, v1, 16, 1
	v_add3_u32 v1, v1, v3, s60
	v_bfe_u32 v3, v2, 16, 1
	v_lshrrev_b32_e32 v1, 16, v1
	v_add3_u32 v2, v2, v3, s60
	v_and_or_b32 v1, v2, s61, v1
	flat_store_dwordx2 v[28:29], v[0:1] offset:3584
	s_cbranch_scc0 .LBB0_183
